# next-unit tile decode shortcut when the grid is 256 (pm unchanged, pn+4) instead of the generic integer-division decode, GU and W_in unit loops
# speedup vs baseline: 1.0147x; 1.0147x over previous
; template <int MODE> __device__ __forceinline__ UD decode(int j) { UD x; x.u = j & 7; int bh; if (MODE == 1) { bh = j >> 4; x.br = 1 + ((j >> 3) & 1); } else { bh = j >> 3; x.br = 0; } x.b = bh / NH; x.h = bh % NH; return x; }
;     __host__ __device__ bool next(int i, Unit& u) const {
;         const long L = (long)i * G + c; if (i >= imax || L >= nwg) return false;
;         decode(L, u); u.par = i & 1; u.roff = 0; return true;
.LBB0_175:
	s_mov_b32 s9, s53
	s_add_i32 s53, s53, 1
	s_mul_i32 s11, s53, s39
	s_mul_hi_u32 s12, s53, s72
	s_add_i32 s11, s12, s11
	s_mul_i32 s12, s53, s72
	s_add_u32 s12, s12, s33
	s_addc_u32 s13, s11, s38
	s_cmp_gt_u32 s9, 0x3ffffffe
	s_cselect_b64 s[14:15], -1, 0
	v_cmp_gt_i64_e32 vcc, s[12:13], v[154:155]
	s_or_b64 s[18:19], s[14:15], vcc
	s_and_b64 vcc, exec, s[18:19]
	s_cbranch_vccnz .LBB0_177
	s_cmpk_lg_u32 s72, 0x100
	s_cbranch_scc1 .Lgu_decode_generic
	s_mov_b32 s10, s57
	s_add_i32 s8, s56, 4
	s_and_b32 s54, s53, 1
	s_branch .LBB0_177
.Lgu_decode_generic:
	s_ashr_i32 s8, s12, 31
	s_lshr_b32 s8, s8, 29
	s_add_i32 s8, s12, s8
	s_ashr_i32 s9, s8, 3
	s_and_b32 s8, s8, -8
	s_sub_i32 s8, s12, s8
	s_cmp_lt_i32 s8, 0
	s_movk_i32 s10, 0xb1
	s_cselect_b32 s10, s10, 0xb0
	s_mul_i32 s8, s8, s10
	s_add_i32 s8, s8, s9
	s_mul_hi_i32 s9, s8, 0x2e8ba2e9
	s_lshr_b32 s10, s9, 31
	s_ashr_i32 s9, s9, 5
	s_add_i32 s9, s9, s10
	s_lshl_b32 s10, s9, 3
	s_sub_i32 s11, 64, s10
	s_min_i32 s11, s11, 8
	s_abs_i32 s12, s11
	v_cvt_f32_u32_e32 v0, s12
	s_sub_i32 s14, 0, s12
	s_mulk_i32 s9, 0xb0
	s_sub_i32 s9, s8, s9
	v_rcp_iflag_f32_e32 v0, v0
	s_abs_i32 s8, s9
	s_xor_b32 s13, s9, s11
	s_ashr_i32 s13, s13, 31
	v_mul_f32_e32 v0, 0x4f7ffffe, v0
	v_cvt_u32_f32_e32 v0, v0
	s_nop 0
	v_readfirstlane_b32 s15, v0
	s_mul_i32 s14, s14, s15
	s_mul_hi_u32 s14, s15, s14
	s_add_i32 s15, s15, s14
	s_mul_hi_u32 s14, s8, s15
	s_mul_i32 s15, s14, s12
	s_sub_i32 s8, s8, s15
	s_add_i32 s16, s14, 1
	s_sub_i32 s15, s8, s12
	s_cmp_ge_u32 s8, s12
	s_cselect_b32 s14, s16, s14
	s_cselect_b32 s8, s15, s8
	s_add_i32 s15, s14, 1
	s_cmp_ge_u32 s8, s12
	s_cselect_b32 s8, s15, s14
	s_xor_b32 s8, s8, s13
	s_sub_i32 s8, s8, s13
	s_mul_i32 s11, s8, s11
	s_sub_i32 s9, s9, s11
	s_add_i32 s10, s10, s9
	s_and_b32 s54, s53, 1

; template <int MODE> __device__ __forceinline__ UD decode(int j) { UD x; x.u = j & 7; int bh; if (MODE == 1) { bh = j >> 4; x.br = 1 + ((j >> 3) & 1); } else { bh = j >> 3; x.br = 0; } x.b = bh / NH; x.h = bh % NH; return x; }
;     __host__ __device__ bool next(int i, Unit& u) const {
;         const long L = (long)i * G + c; if (i >= imax || L >= nwg) return false;
;         decode(L, u); u.par = i & 1; u.roff = 0; return true;
.LBB0_409:
	s_mov_b32 s0, s55
	s_add_i32 s55, s55, 1
	s_mul_i32 s1, s55, s39
	s_mul_hi_u32 s13, s55, s72
	s_add_i32 s13, s13, s1
	s_mul_i32 s1, s55, s72
	s_add_u32 s16, s1, s33
	s_addc_u32 s17, s13, s38
	s_cmp_gt_u32 s0, 0x3ffffffe
	s_cselect_b64 s[0:1], -1, 0
	v_cmp_gt_i64_e32 vcc, s[16:17], v[158:159]
	s_or_b64 s[0:1], s[0:1], vcc
	s_and_b64 vcc, exec, s[0:1]
	s_cbranch_vccnz .LBB0_411
	s_cmpk_lg_u32 s72, 0x100
	s_cbranch_scc1 .Lwi_decode_generic
	s_mov_b32 s14, s58
	s_add_i32 s12, s59, 4
	s_and_b32 s56, s55, 1
	s_branch .LBB0_411
.Lwi_decode_generic:
	s_ashr_i32 s12, s16, 31
	s_lshr_b32 s12, s12, 29
	s_add_i32 s12, s16, s12
	s_ashr_i32 s13, s12, 3
	s_and_b32 s12, s12, -8
	s_sub_i32 s12, s16, s12
	s_cmp_lt_i32 s12, 0
	s_movk_i32 s14, 0x51
	s_cselect_b32 s14, s14, 0x50
	s_mul_i32 s12, s12, s14
	s_add_i32 s12, s12, s13
	s_mul_hi_i32 s13, s12, 0x66666667
	s_lshr_b32 s14, s13, 31
	s_ashr_i32 s13, s13, 5
	s_add_i32 s13, s13, s14
	s_lshl_b32 s14, s13, 3
	s_sub_i32 s15, 64, s14
	s_min_i32 s15, s15, 8
	s_abs_i32 s16, s15
	v_cvt_f32_u32_e32 v0, s16
	s_sub_i32 s18, 0, s16
	s_mulk_i32 s13, 0x50
	s_sub_i32 s13, s12, s13
	v_rcp_iflag_f32_e32 v0, v0
	s_abs_i32 s12, s13
	s_xor_b32 s17, s13, s15
	s_ashr_i32 s17, s17, 31
	v_mul_f32_e32 v0, 0x4f7ffffe, v0
	v_cvt_u32_f32_e32 v0, v0
	s_nop 0
	v_readfirstlane_b32 s19, v0
	s_mul_i32 s18, s18, s19
	s_mul_hi_u32 s18, s19, s18
	s_add_i32 s19, s19, s18
	s_mul_hi_u32 s18, s12, s19
	s_mul_i32 s19, s18, s16
	s_sub_i32 s12, s12, s19
	s_add_i32 s20, s18, 1
	s_sub_i32 s19, s12, s16
	s_cmp_ge_u32 s12, s16
	s_cselect_b32 s18, s20, s18
	s_cselect_b32 s12, s19, s12
	s_add_i32 s19, s18, 1
	s_cmp_ge_u32 s12, s16
	s_cselect_b32 s12, s19, s18
	s_xor_b32 s12, s12, s17
	s_sub_i32 s12, s12, s17
	s_mul_i32 s15, s12, s15
	s_sub_i32 s13, s13, s15
	s_add_i32 s14, s14, s13
	s_and_b32 s56, s55, 1
